# plus: long-conv V staging loops unrolled (all loads issued, counted waits); EpiProj N=2048 epilogue rstd loads hoisted + permlane reductions
# speedup vs baseline: 1.0604x; 1.0022x over previous
; #define LAS __attribute__((address_space(3)))
; __device__ __forceinline__ void longconv_sample2(const Ctx& c, int ch, const bf16_t* vvT, const bf16_t* KR, bf16_t* yT) {
;     ...
;     for (int s = 0; s < NSEQ; ++s) {
;         for (int i = c.tid; i < 96; i += NTHR) { const int idx = i < 32 ? i * 8 : 256 + L + (i - 32) * 8; *(LAS u32x4*)(lds + (s * VLEN + idx) * 2) = (u32x4){0u, 0u, 0u, 0u}; }
;         for (int i = c.tid; i < L / 8; i += NTHR) *(LAS u32x4*)(lds + (s * VLEN + 256 + i * 8) * 2) = *(const u32x4*)(vvT + tok0 + (size_t)s * L + i * 8);
;     }
.LBB1_157:
	v_ashrrev_i32_e32 v1, 31, v0
	v_lshl_add_u64 v[6:7], v[0:1], 1, s[30:31]
	s_mov_b64 s[38:39], 0x2000
	global_load_dwordx4 v[14:17], v[6:7], off
	v_lshl_add_u64 v[6:7], v[6:7], 0, s[38:39]
	global_load_dwordx4 v[18:21], v[6:7], off
	s_waitcnt vmcnt(1)
	ds_write_b128 v2, v[14:17]
	s_waitcnt vmcnt(0)
	ds_write_b128 v2, v[18:21] offset:8192

; #define LAS __attribute__((address_space(3)))
; __device__ __forceinline__ void longconv_sample2(const Ctx& c, int ch, const bf16_t* vvT, const bf16_t* KR, bf16_t* yT) {
;     ...
;     for (int s = 0; s < NSEQ; ++s) {
;         for (int i = c.tid; i < 96; i += NTHR) { const int idx = i < 32 ? i * 8 : 256 + L + (i - 32) * 8; *(LAS u32x4*)(lds + (s * VLEN + idx) * 2) = (u32x4){0u, 0u, 0u, 0u}; }
;         for (int i = c.tid; i < L / 8; i += NTHR) *(LAS u32x4*)(lds + (s * VLEN + 256 + i * 8) * 2) = *(const u32x4*)(vvT + tok0 + (size_t)s * L + i * 8);
;     }
.LBB1_163:
	v_ashrrev_i32_e32 v1, 31, v0
	v_lshl_add_u64 v[6:7], v[0:1], 1, s[38:39]
	s_mov_b64 s[40:41], 0x2000
	global_load_dwordx4 v[14:17], v[6:7], off
	v_lshl_add_u64 v[6:7], v[6:7], 0, s[40:41]
	global_load_dwordx4 v[18:21], v[6:7], off
	s_waitcnt vmcnt(1)
	ds_write_b128 v2, v[14:17]
	s_waitcnt vmcnt(0)
	ds_write_b128 v2, v[18:21] offset:8192

; #define LAS __attribute__((address_space(3)))
; template <bool PROMPT>
; __device__ __forceinline__ void longconv_item(const Ctx& c, int ch, const bf16_t* vvT, const bf16_t* KR, bf16_t* yT) {
;     ...
;     for (int s = 0; s < NSEQ; ++s) {
;         for (int i = c.tid; i < 96; i += NTHR) { const int idx = i < 32 ? i * 8 : 256 + L + (i - 32) * 8; *(LAS u32x4*)(lds + (s * VLEN + idx) * 2) = (u32x4){0u, 0u, 0u, 0u}; }
;         for (int i = c.tid; i < L / 8; i += NTHR) *(LAS u32x4*)(lds + (s * VLEN + 256 + i * 8) * 2) = *(const u32x4*)(vvT + tok0 + (size_t)s * L + i * 8);
;     }
.LBB1_199:
	v_ashrrev_i32_e32 v1, 31, v0
	v_lshl_add_u64 v[6:7], v[0:1], 1, s[30:31]
	s_mov_b64 s[36:37], 0x2000
	global_load_dwordx4 v[10:13], v[6:7], off
	v_lshl_add_u64 v[6:7], v[6:7], 0, s[36:37]
	global_load_dwordx4 v[14:17], v[6:7], off
	v_lshl_add_u64 v[6:7], v[6:7], 0, s[36:37]
	global_load_dwordx4 v[18:21], v[6:7], off
	v_lshl_add_u64 v[6:7], v[6:7], 0, s[36:37]
	global_load_dwordx4 v[22:25], v[6:7], off
	s_waitcnt vmcnt(3)
	ds_write_b128 v2, v[10:13]
	s_waitcnt vmcnt(2)
	ds_write_b128 v2, v[14:17] offset:8192
	s_waitcnt vmcnt(1)
	ds_write_b128 v2, v[18:21] offset:16384
	s_waitcnt vmcnt(0)
	ds_write_b128 v2, v[22:25] offset:24576

; __device__ __forceinline__ unsigned cvt_pk_bf16(float lo, float hi) { unsigned r; asm volatile("v_cvt_pk_bf16_f32 %0, %1, %2" : "=v"(r) : "v"(lo), "v"(hi)); return r; }
; __device__ __forceinline__ float rstd_of4(const float* rss, int row, int fq) {
;     const f32x4 a = *(const f32x4*)(rss + (size_t)row * 16 + 4 * fq); float s = (a[0] + a[1]) + (a[2] + a[3]);
;     s += __shfl_xor(s, 16); s += __shfl_xor(s, 32);
;     return rsqrtf(s * (1.0f / 1024.0f) + EPS); }
;     __device__ __forceinline__ void operator()(const f32x4 (&acc)[2][2][4][2], const Unit& u, int wr, int wc, int fr, int fq, LAS unsigned char* lds) const {
;     ...
;             for (int m = 0; m < 4; ++m) { const int row = row0 + ai * HALF + m * 16; const float rs = rss ? rstd_of4(rss, row, fq) : 1.0f;
; #pragma unroll
;                 for (int bj = 0; bj < 2; ++bj) { const f32x4 v0 = acc[ai][bj][m][0] * rs + bv[bj][0], v1 = acc[ai][bj][m][1] * rs + bv[bj][1];
;                     u32x4 w; w.x = cvt_pk_bf16(v0[0], v0[1]); w.y = cvt_pk_bf16(v0[2], v0[3]); w.z = cvt_pk_bf16(v1[0], v1[1]); w.w = cvt_pk_bf16(v1[2], v1[3]);
;                     *(u32x4*)(O + (size_t)row * ldc + col0 + bj * HALF) = w; } }
.LBB1_722:
	v_readfirstlane_b32 s1, v160
	v_lshl_add_u32 v160, s16, 8, v183
	s_cmp_lg_u64 s[18:19], 0
	s_cselect_b64 s[16:17], -1, 0
	s_cmp_eq_u64 s[18:19], 0
	v_lshl_add_u64 v[158:159], s[18:19], 0, v[4:5]
	v_ashrrev_i32_e32 v161, 31, v160
	v_mov_b32_e32 v164, 1.0
	v_mov_b32_e32 v166, 1.0
	s_cbranch_scc1 .LBB1_724
	v_lshlrev_b64 v[166:167], 6, v[160:161]
	v_lshl_add_u64 v[166:167], v[158:159], 0, v[166:167]
	global_load_dwordx4 v[166:169], v[166:167], off
	v_or_b32_e32 v228, 16, v160
	v_ashrrev_i32_e32 v229, 31, v228
	v_lshlrev_b64 v[228:229], 6, v[228:229]
	v_lshl_add_u64 v[228:229], v[158:159], 0, v[228:229]
	global_load_dwordx4 v[200:203], v[228:229], off
	v_or_b32_e32 v228, 32, v160
	v_ashrrev_i32_e32 v229, 31, v228
	v_lshlrev_b64 v[228:229], 6, v[228:229]
	v_lshl_add_u64 v[228:229], v[158:159], 0, v[228:229]
	global_load_dwordx4 v[204:207], v[228:229], off
	v_or_b32_e32 v228, 48, v160
	v_ashrrev_i32_e32 v229, 31, v228
	v_lshlrev_b64 v[228:229], 6, v[228:229]
	v_lshl_add_u64 v[228:229], v[158:159], 0, v[228:229]
	global_load_dwordx4 v[208:211], v[228:229], off
	v_add_u32_e32 v228, 0x80, v160
	v_ashrrev_i32_e32 v229, 31, v228
	v_lshlrev_b64 v[228:229], 6, v[228:229]
	v_lshl_add_u64 v[228:229], v[158:159], 0, v[228:229]
	global_load_dwordx4 v[212:215], v[228:229], off
	v_add_u32_e32 v228, 0x90, v160
	v_ashrrev_i32_e32 v229, 31, v228
	v_lshlrev_b64 v[228:229], 6, v[228:229]
	v_lshl_add_u64 v[228:229], v[158:159], 0, v[228:229]
	global_load_dwordx4 v[216:219], v[228:229], off
	v_add_u32_e32 v228, 0xa0, v160
	v_ashrrev_i32_e32 v229, 31, v228
	v_lshlrev_b64 v[228:229], 6, v[228:229]
	v_lshl_add_u64 v[228:229], v[158:159], 0, v[228:229]
	global_load_dwordx4 v[220:223], v[228:229], off
	v_add_u32_e32 v228, 0xb0, v160
	v_ashrrev_i32_e32 v229, 31, v228
	v_lshlrev_b64 v[228:229], 6, v[228:229]
	v_lshl_add_u64 v[228:229], v[158:159], 0, v[228:229]
	global_load_dwordx4 v[224:227], v[228:229], off
	s_waitcnt vmcnt(0)
	v_mov_b32_e32 v180, v167
	v_mov_b32_e32 v181, v168
	v_mov_b32_e32 v167, v169
	v_pk_add_f32 v[166:167], v[180:181], v[166:167]
	s_nop 0
	v_add_f32_e32 v161, v166, v167
	v_and_b32_e32 v167, 64, v171
	v_xor_b32_e32 v166, 16, v171
	v_add_u32_e32 v167, 64, v167
	v_cmp_lt_i32_e32 vcc, v166, v167
	s_nop 1
	v_cndmask_b32_e32 v166, v171, v166, vcc
	v_lshlrev_b32_e32 v166, 2, v166
	v_mov_b32_e32 v166, v161
	s_nop 1
	v_permlane16_swap_b32 v166, v161
	s_waitcnt lgkmcnt(0)
	v_add_f32_e32 v161, v161, v166
	v_xor_b32_e32 v166, 32, v171
	v_cmp_lt_i32_e32 vcc, v166, v167
	s_nop 1
	v_cndmask_b32_e32 v166, v171, v166, vcc
	v_lshlrev_b32_e32 v166, 2, v166
	v_mov_b32_e32 v166, v161
	s_nop 1
	v_permlane32_swap_b32 v166, v161
	s_waitcnt lgkmcnt(0)
	v_add_f32_e32 v161, v161, v166
	v_fmamk_f32 v161, v161, 0x3a800000, v173
	v_cmp_gt_f32_e32 vcc, s64, v161
	v_mul_f32_e32 v166, 0x4b800000, v161
	s_nop 0
	v_cndmask_b32_e32 v161, v161, v166, vcc
	v_rsq_f32_e32 v161, v161
	s_nop 0
	v_mul_f32_e32 v166, 0x45800000, v161
	v_cndmask_b32_e32 v166, v161, v166, vcc
.LBB1_724:
	v_mov_b32_e32 v168, s9
	v_mov_b32_e32 v169, s22
	v_lshl_add_u64 v[162:163], v[162:163], 1, v[168:169]
	v_mad_i64_i32 v[168:169], s[6:7], s1, v160, 0
	v_lshl_add_u64 v[168:169], v[168:169], 1, v[162:163]
	v_pk_fma_f32 v[142:143], v[142:143], v[166:167], v[156:157] op_sel_hi:[1,0,1]
	v_pk_fma_f32 v[140:141], v[140:141], v[166:167], v[94:95] op_sel_hi:[1,0,1]
	s_waitcnt vmcnt(0)
	v_pk_fma_f32 v[180:181], v[138:139], v[166:167], v[92:93] op_sel_hi:[1,0,1]
	v_pk_fma_f32 v[138:139], v[136:137], v[166:167], v[90:91] op_sel_hi:[1,0,1]
	v_cvt_pk_bf16_f32 v136, v140, v141
	v_cvt_pk_bf16_f32 v137, v142, v143
	v_pk_fma_f32 v[134:135], v[134:135], v[166:167], v[102:103] op_sel_hi:[1,0,1]
	v_cvt_pk_bf16_f32 v138, v138, v139
	v_cvt_pk_bf16_f32 v139, v180, v181
	global_store_dwordx4 v[168:169], v[136:139], off
	v_pk_fma_f32 v[132:133], v[132:133], v[166:167], v[100:101] op_sel_hi:[1,0,1]
	s_andn2_b64 vcc, exec, s[16:17]
	v_pk_fma_f32 v[136:137], v[130:131], v[166:167], v[98:99] op_sel_hi:[1,0,1]
	v_pk_fma_f32 v[130:131], v[128:129], v[166:167], v[96:97] op_sel_hi:[1,0,1]
	v_cvt_pk_bf16_f32 v128, v132, v133
	v_cvt_pk_bf16_f32 v129, v134, v135
	s_nop 0
	v_cvt_pk_bf16_f32 v130, v130, v131
	v_cvt_pk_bf16_f32 v131, v136, v137
	global_store_dwordx4 v[168:169], v[128:131], off offset:256
	s_nop 1
	v_or_b32_e32 v128, 16, v160
	v_cndmask_b32_e64 v129, 0, 1, s[16:17]
	v_cmp_ne_u32_e64 s[6:7], 1, v129
	v_ashrrev_i32_e32 v129, 31, v128
	s_cbranch_vccnz .LBB1_726
	v_lshlrev_b64 v[130:131], 6, v[128:129]
	v_lshl_add_u64 v[130:131], v[158:159], 0, v[130:131]
	v_mov_b32_e32 v130, v200
	v_mov_b32_e32 v131, v201
	v_mov_b32_e32 v132, v202
	v_mov_b32_e32 v133, v203
	s_nop 0
	v_mov_b32_e32 v134, v131
	v_mov_b32_e32 v135, v132
	v_mov_b32_e32 v131, v133
	v_pk_add_f32 v[130:131], v[134:135], v[130:131]
	s_nop 0
	v_add_f32_e32 v129, v130, v131
	v_and_b32_e32 v131, 64, v171
	v_xor_b32_e32 v130, 16, v171
	v_add_u32_e32 v131, 64, v131
	v_cmp_lt_i32_e32 vcc, v130, v131
	s_nop 1
	v_cndmask_b32_e32 v130, v171, v130, vcc
	v_lshlrev_b32_e32 v130, 2, v130
	v_mov_b32_e32 v130, v129
	s_nop 1
	v_permlane16_swap_b32 v130, v129
	s_waitcnt lgkmcnt(0)
	v_add_f32_e32 v129, v129, v130
	v_xor_b32_e32 v130, 32, v171
	v_cmp_lt_i32_e32 vcc, v130, v131
	s_nop 1
	v_cndmask_b32_e32 v130, v171, v130, vcc
	v_lshlrev_b32_e32 v130, 2, v130
	v_mov_b32_e32 v130, v129
	s_nop 1
	v_permlane32_swap_b32 v130, v129
	s_waitcnt lgkmcnt(0)
	v_add_f32_e32 v129, v129, v130
	v_fmamk_f32 v129, v129, 0x3a800000, v173
	v_cmp_gt_f32_e32 vcc, s64, v129
	v_mul_f32_e32 v130, 0x4b800000, v129
	s_nop 0
	v_cndmask_b32_e32 v129, v129, v130, vcc
	v_rsq_f32_e32 v129, v129
	s_nop 0
	v_mul_f32_e32 v130, 0x45800000, v129
	v_cndmask_b32_e32 v164, v129, v130, vcc

; __device__ __forceinline__ unsigned cvt_pk_bf16(float lo, float hi) { unsigned r; asm volatile("v_cvt_pk_bf16_f32 %0, %1, %2" : "=v"(r) : "v"(lo), "v"(hi)); return r; }
; __device__ __forceinline__ float rstd_of4(const float* rss, int row, int fq) {
;     const f32x4 a = *(const f32x4*)(rss + (size_t)row * 16 + 4 * fq); float s = (a[0] + a[1]) + (a[2] + a[3]);
;     s += __shfl_xor(s, 16); s += __shfl_xor(s, 32);
;     return rsqrtf(s * (1.0f / 1024.0f) + EPS); }
;     __device__ __forceinline__ void operator()(const f32x4 (&acc)[2][2][4][2], const Unit& u, int wr, int wc, int fr, int fq, LAS unsigned char* lds) const {
;     ...
;             for (int m = 0; m < 4; ++m) { const int row = row0 + ai * HALF + m * 16; const float rs = rss ? rstd_of4(rss, row, fq) : 1.0f;
; #pragma unroll
;                 for (int bj = 0; bj < 2; ++bj) { const f32x4 v0 = acc[ai][bj][m][0] * rs + bv[bj][0], v1 = acc[ai][bj][m][1] * rs + bv[bj][1];
;                     u32x4 w; w.x = cvt_pk_bf16(v0[0], v0[1]); w.y = cvt_pk_bf16(v0[2], v0[3]); w.z = cvt_pk_bf16(v1[0], v1[1]); w.w = cvt_pk_bf16(v1[2], v1[3]);
;                     *(u32x4*)(O + (size_t)row * ldc + col0 + bj * HALF) = w; } }
.LBB1_736:
	v_mad_i64_i32 v[36:37], s[16:17], s1, v36, 0
	v_lshl_add_u64 v[36:37], v[36:37], 1, v[162:163]
	v_pk_fma_f32 v[32:33], v[32:33], v[38:39], v[156:157] op_sel_hi:[1,0,1]
	v_pk_fma_f32 v[30:31], v[30:31], v[38:39], v[94:95] op_sel_hi:[1,0,1]
	v_pk_fma_f32 v[40:41], v[28:29], v[38:39], v[92:93] op_sel_hi:[1,0,1]
	v_pk_fma_f32 v[28:29], v[26:27], v[38:39], v[90:91] op_sel_hi:[1,0,1]
	v_cvt_pk_bf16_f32 v26, v30, v31
	v_cvt_pk_bf16_f32 v27, v32, v33
	v_pk_fma_f32 v[22:23], v[22:23], v[38:39], v[100:101] op_sel_hi:[1,0,1]
	v_cvt_pk_bf16_f32 v28, v28, v29
	v_cvt_pk_bf16_f32 v29, v40, v41
	global_store_dwordx4 v[36:37], v[26:29], off
	v_pk_fma_f32 v[24:25], v[24:25], v[38:39], v[102:103] op_sel_hi:[1,0,1]
	s_and_b64 vcc, exec, s[6:7]
	v_pk_fma_f32 v[26:27], v[20:21], v[38:39], v[98:99] op_sel_hi:[1,0,1]
	v_pk_fma_f32 v[20:21], v[18:19], v[38:39], v[96:97] op_sel_hi:[1,0,1]
	v_cvt_pk_bf16_f32 v18, v22, v23
	v_cvt_pk_bf16_f32 v19, v24, v25
	s_nop 0
	v_cvt_pk_bf16_f32 v20, v20, v21
	v_cvt_pk_bf16_f32 v21, v26, v27
	global_store_dwordx4 v[36:37], v[18:21], off offset:256
	s_nop 1
	v_add_u32_e32 v18, 0xb0, v160
	v_ashrrev_i32_e32 v19, 31, v18
	s_cbranch_vccnz .LBB1_709
	v_lshlrev_b64 v[20:21], 6, v[18:19]
	v_lshl_add_u64 v[20:21], v[158:159], 0, v[20:21]
	v_mov_b32_e32 v20, v224
	v_mov_b32_e32 v21, v225
	v_mov_b32_e32 v22, v226
	v_mov_b32_e32 v23, v227
	s_nop 0
	v_mov_b32_e32 v24, v21
	v_mov_b32_e32 v25, v22
	v_mov_b32_e32 v21, v23
	v_pk_add_f32 v[20:21], v[24:25], v[20:21]
	s_nop 0
	v_add_f32_e32 v19, v20, v21
	v_and_b32_e32 v21, 64, v171
	v_xor_b32_e32 v20, 16, v171
	v_add_u32_e32 v21, 64, v21
	v_cmp_lt_i32_e32 vcc, v20, v21
	s_nop 1
	v_cndmask_b32_e32 v20, v171, v20, vcc
	v_lshlrev_b32_e32 v20, 2, v20
	v_mov_b32_e32 v20, v19
	s_nop 1
	v_permlane16_swap_b32 v20, v19
	s_waitcnt lgkmcnt(0)
	v_add_f32_e32 v19, v19, v20
	v_xor_b32_e32 v20, 32, v171
	v_cmp_lt_i32_e32 vcc, v20, v21
	s_nop 1
	v_cndmask_b32_e32 v20, v171, v20, vcc
	v_lshlrev_b32_e32 v20, 2, v20
	v_mov_b32_e32 v20, v19
	s_nop 1
	v_permlane32_swap_b32 v20, v19
	s_waitcnt lgkmcnt(0)
	v_add_f32_e32 v19, v19, v20
	v_fmamk_f32 v19, v19, 0x3a800000, v173
	v_cmp_gt_f32_e32 vcc, s64, v19
	v_mul_f32_e32 v20, 0x4b800000, v19
	s_nop 0
	v_cndmask_b32_e32 v19, v19, v20, vcc
	v_rsq_f32_e32 v19, v19
	s_nop 0
	v_mul_f32_e32 v20, 0x45800000, v19
	v_cndmask_b32_e32 v34, v19, v20, vcc
	s_branch .LBB1_709
.LBB1_738:
	s_waitcnt vmcnt(0)
	s_cmpk_gt_u32 s26, 0xff
	s_cbranch_scc1 .LBB1_740
	s_barrier
